# K-loop: barrier B moved 4 MFMAs earlier in each MFMA segment so the partner half starts its MFMAs while the last 4 drain (hide handoff bubble)
# baseline (speedup 1.0000x reference)
.LBB0_390:
	s_add_u32 s38, s42, 0x100
	s_addc_u32 s39, s43, 0
	s_add_i32 s4, 0, 0x10000
	s_cmp_eq_u32 s73, 12
	s_cselect_b32 s69, s29, s39
	s_cselect_b32 s68, vcc_lo, s38
	s_cselect_b32 s67, s37, s72
	s_cselect_b32 s66, vcc_hi, s59
	s_add_i32 s6, 0, 0x14000
	v_add_u32_e32 v142, s4, v251
	v_add_u32_e32 v158, s6, v251
	ds_read_b128 v[130:133], v142
	ds_read_b128 v[134:137], v142 offset:1024
	ds_read_b128 v[138:141], v142 offset:2048
	ds_read_b128 v[142:145], v142 offset:3072
	ds_read_b128 v[146:149], v158
	ds_read_b128 v[150:153], v158 offset:1024
	ds_read_b128 v[154:157], v158 offset:2048
	ds_read_b128 v[158:161], v158 offset:3072
	v_lshl_add_u64 v[194:195], s[42:43], 0, v[228:229]
	s_add_i32 m0, s75, 0xc000
	ds_read_b128 v[162:165], v244
	ds_read_b128 v[166:169], v244 offset:1024
	ds_read_b128 v[170:173], v244 offset:2048
	ds_read_b128 v[174:177], v244 offset:3072
	ds_read_b128 v[178:181], v244 offset:4096
	ds_read_b128 v[182:185], v244 offset:5120
	ds_read_b128 v[186:189], v244 offset:6144
	ds_read_b128 v[190:193], v244 offset:7168
	global_load_lds_dwordx4 v[194:195], off
	v_lshl_add_u64 v[194:195], s[42:43], 0, v[230:231]
	s_add_i32 m0, s75, 0xe000
	s_nop 0
	global_load_lds_dwordx4 v[194:195], off
	s_waitcnt vmcnt(8)
	s_waitcnt lgkmcnt(0)
	s_barrier
	s_setprio 1
	s_waitcnt lgkmcnt(0)
	v_mfma_f32_16x16x32_bf16 v[114:117], v[130:133], v[162:165], v[114:117]
	v_mfma_f32_16x16x32_bf16 v[122:125], v[138:141], v[162:165], v[122:125]
	v_mfma_f32_16x16x32_bf16 v[118:121], v[130:133], v[170:173], v[118:121]
	v_mfma_f32_16x16x32_bf16 v[126:129], v[138:141], v[170:173], v[126:129]
	v_mfma_f32_16x16x32_bf16 v[54:57], v[130:133], v[178:181], v[54:57]
	v_mfma_f32_16x16x32_bf16 v[70:73], v[138:141], v[178:181], v[70:73]
	v_mfma_f32_16x16x32_bf16 v[50:53], v[130:133], v[186:189], v[50:53]
	v_mfma_f32_16x16x32_bf16 v[66:69], v[138:141], v[186:189], v[66:69]
	v_mfma_f32_16x16x32_bf16 v[114:117], v[134:137], v[166:169], v[114:117]
	v_mfma_f32_16x16x32_bf16 v[122:125], v[142:145], v[166:169], v[122:125]
	v_mfma_f32_16x16x32_bf16 v[118:121], v[134:137], v[174:177], v[118:121]
	v_mfma_f32_16x16x32_bf16 v[126:129], v[142:145], v[174:177], v[126:129]
	v_mfma_f32_16x16x32_bf16 v[54:57], v[134:137], v[182:185], v[54:57]
	v_mfma_f32_16x16x32_bf16 v[70:73], v[142:145], v[182:185], v[70:73]
	v_mfma_f32_16x16x32_bf16 v[50:53], v[134:137], v[190:193], v[50:53]
	v_mfma_f32_16x16x32_bf16 v[66:69], v[142:145], v[190:193], v[66:69]
	s_setprio 0
	s_setprio 1
	v_mfma_f32_16x16x32_bf16 v[106:109], v[146:149], v[162:165], v[106:109]
	v_mfma_f32_16x16x32_bf16 v[42:45], v[154:157], v[162:165], v[42:45]
	v_mfma_f32_16x16x32_bf16 v[110:113], v[146:149], v[170:173], v[110:113]
	v_mfma_f32_16x16x32_bf16 v[46:49], v[154:157], v[170:173], v[46:49]
	v_mfma_f32_16x16x32_bf16 v[30:33], v[146:149], v[178:181], v[30:33]
	v_mfma_f32_16x16x32_bf16 v[14:17], v[154:157], v[178:181], v[14:17]
	v_mfma_f32_16x16x32_bf16 v[26:29], v[146:149], v[186:189], v[26:29]
	v_mfma_f32_16x16x32_bf16 v[10:13], v[154:157], v[186:189], v[10:13]
	v_mfma_f32_16x16x32_bf16 v[106:109], v[150:153], v[166:169], v[106:109]
	v_mfma_f32_16x16x32_bf16 v[42:45], v[158:161], v[166:169], v[42:45]
	v_mfma_f32_16x16x32_bf16 v[110:113], v[150:153], v[174:177], v[110:113]
	v_mfma_f32_16x16x32_bf16 v[46:49], v[158:161], v[174:177], v[46:49]
	s_barrier
	v_mfma_f32_16x16x32_bf16 v[30:33], v[150:153], v[182:185], v[30:33]
	v_mfma_f32_16x16x32_bf16 v[14:17], v[158:161], v[182:185], v[14:17]
	v_mfma_f32_16x16x32_bf16 v[26:29], v[150:153], v[190:193], v[26:29]
	v_mfma_f32_16x16x32_bf16 v[10:13], v[158:161], v[190:193], v[10:13]
	s_setprio 0
	s_add_i32 s4, s4, s74
	v_lshl_add_u64 v[194:195], s[66:67], 0, v[0:1]
	s_mov_b32 m0, s4
	ds_read_b128 v[162:165], v244 offset:16384
	ds_read_b128 v[166:169], v244 offset:17408
	ds_read_b128 v[170:173], v244 offset:18432
	ds_read_b128 v[174:177], v244 offset:19456
	ds_read_b128 v[178:181], v244 offset:20480
	ds_read_b128 v[182:185], v244 offset:21504
	ds_read_b128 v[186:189], v244 offset:22528
	ds_read_b128 v[190:193], v244 offset:23552
	global_load_lds_dwordx4 v[194:195], off
	s_add_i32 m0, s4, 0x2000
	s_add_u32 s4, s66, 0x40000
	v_lshl_add_u64 v[196:197], s[66:67], 0, v[224:225]
	s_addc_u32 s5, s67, 0
	s_add_i32 s6, s6, s74
	global_load_lds_dwordx4 v[196:197], off
	v_lshl_add_u64 v[198:199], s[4:5], 0, v[0:1]
	s_mov_b32 m0, s6
	v_lshl_add_u64 v[200:201], s[68:69], 0, v[222:223]
	global_load_lds_dwordx4 v[198:199], off
	v_lshl_add_u64 v[198:199], s[4:5], 0, v[224:225]
	s_add_i32 m0, s6, 0x2000
	s_nop 0
	global_load_lds_dwordx4 v[198:199], off
	v_lshl_add_u64 v[198:199], s[68:69], 0, v[226:227]
	s_mov_b32 m0, s75
	s_nop 0
	global_load_lds_dwordx4 v[198:199], off
	s_mov_b32 m0, s76
	s_nop 0
	global_load_lds_dwordx4 v[200:201], off
	s_waitcnt vmcnt(8)
	s_waitcnt lgkmcnt(0)
	s_barrier
	s_setprio 1
	s_waitcnt lgkmcnt(0)
	v_mfma_f32_16x16x32_bf16 v[38:41], v[130:133], v[162:165], v[38:41]
	v_mfma_f32_16x16x32_bf16 v[62:65], v[138:141], v[162:165], v[62:65]
	v_mfma_f32_16x16x32_bf16 v[34:37], v[130:133], v[170:173], v[34:37]
	v_mfma_f32_16x16x32_bf16 v[58:61], v[138:141], v[170:173], v[58:61]
	v_mfma_f32_16x16x32_bf16 v[102:105], v[130:133], v[178:181], v[102:105]
	v_mfma_f32_16x16x32_bf16 v[98:101], v[138:141], v[178:181], v[98:101]
	v_mfma_f32_16x16x32_bf16 v[94:97], v[130:133], v[186:189], v[94:97]
	v_mfma_f32_16x16x32_bf16 v[90:93], v[138:141], v[186:189], v[90:93]
	v_mfma_f32_16x16x32_bf16 v[38:41], v[134:137], v[166:169], v[38:41]
	v_mfma_f32_16x16x32_bf16 v[62:65], v[142:145], v[166:169], v[62:65]
	v_mfma_f32_16x16x32_bf16 v[34:37], v[134:137], v[174:177], v[34:37]
	v_mfma_f32_16x16x32_bf16 v[58:61], v[142:145], v[174:177], v[58:61]
	v_mfma_f32_16x16x32_bf16 v[102:105], v[134:137], v[182:185], v[102:105]
	v_mfma_f32_16x16x32_bf16 v[98:101], v[142:145], v[182:185], v[98:101]
	v_mfma_f32_16x16x32_bf16 v[94:97], v[134:137], v[190:193], v[94:97]
	v_mfma_f32_16x16x32_bf16 v[90:93], v[142:145], v[190:193], v[90:93]
	s_setprio 0
	s_setprio 1
	v_mfma_f32_16x16x32_bf16 v[22:25], v[146:149], v[162:165], v[22:25]
	v_mfma_f32_16x16x32_bf16 v[6:9], v[154:157], v[162:165], v[6:9]
	v_mfma_f32_16x16x32_bf16 v[18:21], v[146:149], v[170:173], v[18:21]
	v_mfma_f32_16x16x32_bf16 v[2:5], v[154:157], v[170:173], v[2:5]
	v_mfma_f32_16x16x32_bf16 v[86:89], v[146:149], v[178:181], v[86:89]
	v_mfma_f32_16x16x32_bf16 v[82:85], v[154:157], v[178:181], v[82:85]
	v_mfma_f32_16x16x32_bf16 v[78:81], v[146:149], v[186:189], v[78:81]
	v_mfma_f32_16x16x32_bf16 v[74:77], v[154:157], v[186:189], v[74:77]
	v_mfma_f32_16x16x32_bf16 v[22:25], v[150:153], v[166:169], v[22:25]
	v_mfma_f32_16x16x32_bf16 v[6:9], v[158:161], v[166:169], v[6:9]
	v_mfma_f32_16x16x32_bf16 v[18:21], v[150:153], v[174:177], v[18:21]
	v_mfma_f32_16x16x32_bf16 v[2:5], v[158:161], v[174:177], v[2:5]
	s_barrier
	v_mfma_f32_16x16x32_bf16 v[86:89], v[150:153], v[182:185], v[86:89]
	v_mfma_f32_16x16x32_bf16 v[82:85], v[158:161], v[182:185], v[82:85]
	v_mfma_f32_16x16x32_bf16 v[78:81], v[150:153], v[190:193], v[78:81]
	v_mfma_f32_16x16x32_bf16 v[74:77], v[158:161], v[190:193], v[74:77]
	s_setprio 0
	s_add_i32 s6, 0, 0x18000
	s_add_i32 s7, 0, 0x1c000
	v_add_u32_e32 v142, s6, v251
	v_add_u32_e32 v158, s7, v251
	ds_read_b128 v[130:133], v142
	ds_read_b128 v[134:137], v142 offset:1024
	ds_read_b128 v[138:141], v142 offset:2048
	ds_read_b128 v[142:145], v142 offset:3072
	ds_read_b128 v[146:149], v158
	ds_read_b128 v[150:153], v158 offset:1024
	ds_read_b128 v[154:157], v158 offset:2048
	ds_read_b128 v[158:161], v158 offset:3072
	s_add_u32 s4, s68, 0x2000
	s_addc_u32 s5, s69, 0
	s_mov_b32 m0, s77
	v_lshl_add_u64 v[202:203], s[4:5], 0, v[226:227]
	ds_read_b128 v[162:165], v244 offset:32768
	ds_read_b128 v[166:169], v244 offset:33792
	ds_read_b128 v[170:173], v244 offset:34816
	ds_read_b128 v[174:177], v244 offset:35840
	ds_read_b128 v[178:181], v244 offset:36864
	ds_read_b128 v[182:185], v244 offset:37888
	ds_read_b128 v[186:189], v244 offset:38912
	ds_read_b128 v[190:193], v244 offset:39936
	global_load_lds_dwordx4 v[202:203], off
	v_lshl_add_u64 v[202:203], s[4:5], 0, v[222:223]
	s_mov_b32 m0, s78
	s_nop 0
	global_load_lds_dwordx4 v[202:203], off
	s_waitcnt vmcnt(8)
	s_waitcnt lgkmcnt(0)
	s_barrier
	s_setprio 1
	s_waitcnt lgkmcnt(0)
	v_mfma_f32_16x16x32_bf16 v[114:117], v[130:133], v[162:165], v[114:117]
	v_mfma_f32_16x16x32_bf16 v[122:125], v[138:141], v[162:165], v[122:125]
	v_mfma_f32_16x16x32_bf16 v[118:121], v[130:133], v[170:173], v[118:121]
	v_mfma_f32_16x16x32_bf16 v[126:129], v[138:141], v[170:173], v[126:129]
	v_mfma_f32_16x16x32_bf16 v[54:57], v[130:133], v[178:181], v[54:57]
	v_mfma_f32_16x16x32_bf16 v[70:73], v[138:141], v[178:181], v[70:73]
	v_mfma_f32_16x16x32_bf16 v[50:53], v[130:133], v[186:189], v[50:53]
	v_mfma_f32_16x16x32_bf16 v[66:69], v[138:141], v[186:189], v[66:69]
	v_mfma_f32_16x16x32_bf16 v[114:117], v[134:137], v[166:169], v[114:117]
	v_mfma_f32_16x16x32_bf16 v[122:125], v[142:145], v[166:169], v[122:125]
	v_mfma_f32_16x16x32_bf16 v[118:121], v[134:137], v[174:177], v[118:121]
	v_mfma_f32_16x16x32_bf16 v[126:129], v[142:145], v[174:177], v[126:129]
	v_mfma_f32_16x16x32_bf16 v[54:57], v[134:137], v[182:185], v[54:57]
	v_mfma_f32_16x16x32_bf16 v[70:73], v[142:145], v[182:185], v[70:73]
	v_mfma_f32_16x16x32_bf16 v[50:53], v[134:137], v[190:193], v[50:53]
	v_mfma_f32_16x16x32_bf16 v[66:69], v[142:145], v[190:193], v[66:69]
	s_setprio 0
	s_setprio 1
	v_mfma_f32_16x16x32_bf16 v[106:109], v[146:149], v[162:165], v[106:109]
	v_mfma_f32_16x16x32_bf16 v[42:45], v[154:157], v[162:165], v[42:45]
	v_mfma_f32_16x16x32_bf16 v[110:113], v[146:149], v[170:173], v[110:113]
	v_mfma_f32_16x16x32_bf16 v[46:49], v[154:157], v[170:173], v[46:49]
	v_mfma_f32_16x16x32_bf16 v[30:33], v[146:149], v[178:181], v[30:33]
	v_mfma_f32_16x16x32_bf16 v[14:17], v[154:157], v[178:181], v[14:17]
	v_mfma_f32_16x16x32_bf16 v[26:29], v[146:149], v[186:189], v[26:29]
	v_mfma_f32_16x16x32_bf16 v[10:13], v[154:157], v[186:189], v[10:13]
	v_mfma_f32_16x16x32_bf16 v[106:109], v[150:153], v[166:169], v[106:109]
	v_mfma_f32_16x16x32_bf16 v[42:45], v[158:161], v[166:169], v[42:45]
	v_mfma_f32_16x16x32_bf16 v[110:113], v[150:153], v[174:177], v[110:113]
	v_mfma_f32_16x16x32_bf16 v[46:49], v[158:161], v[174:177], v[46:49]
	s_barrier
	v_mfma_f32_16x16x32_bf16 v[30:33], v[150:153], v[182:185], v[30:33]
	v_mfma_f32_16x16x32_bf16 v[14:17], v[158:161], v[182:185], v[14:17]
	v_mfma_f32_16x16x32_bf16 v[26:29], v[150:153], v[190:193], v[26:29]
	v_mfma_f32_16x16x32_bf16 v[10:13], v[158:161], v[190:193], v[10:13]
	s_setprio 0
	s_add_i32 s4, s6, s74
	v_lshl_add_u64 v[194:195], v[194:195], 0, s[82:83]
	s_mov_b32 m0, s4
	ds_read_b128 v[162:165], v244 offset:49152
	ds_read_b128 v[166:169], v244 offset:50176
	ds_read_b128 v[170:173], v244 offset:51200
	ds_read_b128 v[174:177], v244 offset:52224
	ds_read_b128 v[178:181], v244 offset:53248
	ds_read_b128 v[182:185], v244 offset:54272
	ds_read_b128 v[186:189], v244 offset:55296
	ds_read_b128 v[190:193], v244 offset:56320
	global_load_lds_dwordx4 v[194:195], off
	s_add_i32 m0, s4, 0x2000
	s_add_u32 s4, s66, 0x40080
	v_lshl_add_u64 v[194:195], v[196:197], 0, s[82:83]
	s_addc_u32 s5, s67, 0
	s_add_i32 s6, s7, s74
	global_load_lds_dwordx4 v[194:195], off
	v_lshl_add_u64 v[194:195], s[4:5], 0, v[0:1]
	s_mov_b32 m0, s6
	s_nop 0
	global_load_lds_dwordx4 v[194:195], off
	v_lshl_add_u64 v[194:195], s[4:5], 0, v[224:225]
	s_add_i32 m0, s6, 0x2000
	s_nop 0
	global_load_lds_dwordx4 v[194:195], off
	v_lshl_add_u64 v[194:195], v[198:199], 0, s[82:83]
	s_mov_b32 m0, s94
	s_nop 0
	global_load_lds_dwordx4 v[194:195], off
	v_lshl_add_u64 v[194:195], v[200:201], 0, s[82:83]
	s_mov_b32 m0, s95
	s_nop 0
	global_load_lds_dwordx4 v[194:195], off
	s_waitcnt vmcnt(8)
	s_waitcnt lgkmcnt(0)
	s_barrier
	s_setprio 1
	s_waitcnt lgkmcnt(0)
	v_mfma_f32_16x16x32_bf16 v[38:41], v[130:133], v[162:165], v[38:41]
	v_mfma_f32_16x16x32_bf16 v[62:65], v[138:141], v[162:165], v[62:65]
	v_mfma_f32_16x16x32_bf16 v[34:37], v[130:133], v[170:173], v[34:37]
	v_mfma_f32_16x16x32_bf16 v[58:61], v[138:141], v[170:173], v[58:61]
	v_mfma_f32_16x16x32_bf16 v[102:105], v[130:133], v[178:181], v[102:105]
	v_mfma_f32_16x16x32_bf16 v[98:101], v[138:141], v[178:181], v[98:101]
	v_mfma_f32_16x16x32_bf16 v[94:97], v[130:133], v[186:189], v[94:97]
	v_mfma_f32_16x16x32_bf16 v[90:93], v[138:141], v[186:189], v[90:93]
	v_mfma_f32_16x16x32_bf16 v[38:41], v[134:137], v[166:169], v[38:41]
	v_mfma_f32_16x16x32_bf16 v[62:65], v[142:145], v[166:169], v[62:65]
	v_mfma_f32_16x16x32_bf16 v[34:37], v[134:137], v[174:177], v[34:37]
	v_mfma_f32_16x16x32_bf16 v[58:61], v[142:145], v[174:177], v[58:61]
	v_mfma_f32_16x16x32_bf16 v[102:105], v[134:137], v[182:185], v[102:105]
	v_mfma_f32_16x16x32_bf16 v[98:101], v[142:145], v[182:185], v[98:101]
	v_mfma_f32_16x16x32_bf16 v[94:97], v[134:137], v[190:193], v[94:97]
	v_mfma_f32_16x16x32_bf16 v[90:93], v[142:145], v[190:193], v[90:93]
	s_setprio 0
	s_setprio 1
	v_mfma_f32_16x16x32_bf16 v[22:25], v[146:149], v[162:165], v[22:25]
	v_mfma_f32_16x16x32_bf16 v[6:9], v[154:157], v[162:165], v[6:9]
	v_mfma_f32_16x16x32_bf16 v[18:21], v[146:149], v[170:173], v[18:21]
	v_mfma_f32_16x16x32_bf16 v[2:5], v[154:157], v[170:173], v[2:5]
	v_mfma_f32_16x16x32_bf16 v[86:89], v[146:149], v[178:181], v[86:89]
	v_mfma_f32_16x16x32_bf16 v[82:85], v[154:157], v[178:181], v[82:85]
	v_mfma_f32_16x16x32_bf16 v[78:81], v[146:149], v[186:189], v[78:81]
	v_mfma_f32_16x16x32_bf16 v[74:77], v[154:157], v[186:189], v[74:77]
	v_mfma_f32_16x16x32_bf16 v[22:25], v[150:153], v[166:169], v[22:25]
	v_mfma_f32_16x16x32_bf16 v[6:9], v[158:161], v[166:169], v[6:9]
	v_mfma_f32_16x16x32_bf16 v[18:21], v[150:153], v[174:177], v[18:21]
	v_mfma_f32_16x16x32_bf16 v[2:5], v[158:161], v[174:177], v[2:5]
	s_barrier
	v_mfma_f32_16x16x32_bf16 v[86:89], v[150:153], v[182:185], v[86:89]
	v_mfma_f32_16x16x32_bf16 v[82:85], v[158:161], v[182:185], v[82:85]
	v_mfma_f32_16x16x32_bf16 v[78:81], v[150:153], v[190:193], v[78:81]
	v_mfma_f32_16x16x32_bf16 v[74:77], v[158:161], v[190:193], v[74:77]
	s_setprio 0
	s_add_i32 s73, s73, 2
	s_add_u32 s59, s59, 0x100
	s_addc_u32 s72, s72, 0
	s_cmp_gt_u32 s73, 13
	s_mov_b64 s[42:43], s[38:39]
	s_cbranch_scc0 .LBB0_390
	s_and_b64 vcc, exec, s[50:51]
	s_cbranch_vccz .LBB0_393
	s_barrier

.LBB0_452:
	s_add_i32 s59, s34, 2
	s_add_u32 s4, s30, 0x80
	s_addc_u32 s5, s31, 0
	s_add_i32 s6, 0, 0x10000
	s_cmp_eq_u32 s53, s34
	s_cselect_b32 s35, s27, s5
	s_cselect_b32 s34, s26, s4
	s_cselect_b32 s5, s29, s43
	s_cselect_b32 s4, s28, s42
	s_add_i32 s7, 0, 0x14000
	v_add_u32_e32 v142, s6, v184
	v_add_u32_e32 v168, s7, v184
	ds_read_b128 v[130:133], v142
	ds_read_b128 v[134:137], v142 offset:1024
	ds_read_b128 v[138:141], v142 offset:2048
	ds_read_b128 v[142:145], v142 offset:3072
	ds_read_b128 v[146:149], v168
	ds_read_b128 v[150:153], v168 offset:1024
	ds_read_b128 v[154:157], v168 offset:2048
	ds_read_b128 v[168:171], v168 offset:3072
	v_lshl_add_u64 v[180:181], s[30:31], 0, v[164:165]
	s_add_i32 m0, s38, 0xc000
	ds_read_b128 v[172:175], v187
	ds_read_b128 v[176:179], v187 offset:1024
	ds_read_b128 v[188:191], v187 offset:2048
	ds_read_b128 v[192:195], v187 offset:3072
	ds_read_b128 v[196:199], v187 offset:4096
	ds_read_b128 v[200:203], v187 offset:5120
	ds_read_b128 v[204:207], v187 offset:6144
	ds_read_b128 v[222:225], v187 offset:7168
	global_load_lds_dwordx4 v[180:181], off
	v_lshl_add_u64 v[180:181], s[30:31], 0, v[166:167]
	s_add_i32 m0, s38, 0xe000
	s_nop 0
	global_load_lds_dwordx4 v[180:181], off
	s_waitcnt vmcnt(8)
	s_waitcnt lgkmcnt(0)
	s_barrier
	s_setprio 1
	s_waitcnt lgkmcnt(0)
	v_mfma_f32_16x16x32_bf16 v[126:129], v[130:133], v[172:175], v[126:129]
	v_mfma_f32_16x16x32_bf16 v[122:125], v[138:141], v[172:175], v[122:125]
	v_mfma_f32_16x16x32_bf16 v[110:113], v[130:133], v[188:191], v[110:113]
	v_mfma_f32_16x16x32_bf16 v[106:109], v[138:141], v[188:191], v[106:109]
	v_mfma_f32_16x16x32_bf16 v[98:101], v[130:133], v[196:199], v[98:101]
	v_mfma_f32_16x16x32_bf16 v[90:93], v[138:141], v[196:199], v[90:93]
	v_mfma_f32_16x16x32_bf16 v[82:85], v[130:133], v[204:207], v[82:85]
	v_mfma_f32_16x16x32_bf16 v[74:77], v[138:141], v[204:207], v[74:77]
	v_mfma_f32_16x16x32_bf16 v[126:129], v[134:137], v[176:179], v[126:129]
	v_mfma_f32_16x16x32_bf16 v[122:125], v[142:145], v[176:179], v[122:125]
	v_mfma_f32_16x16x32_bf16 v[110:113], v[134:137], v[192:195], v[110:113]
	v_mfma_f32_16x16x32_bf16 v[106:109], v[142:145], v[192:195], v[106:109]
	v_mfma_f32_16x16x32_bf16 v[98:101], v[134:137], v[200:203], v[98:101]
	v_mfma_f32_16x16x32_bf16 v[90:93], v[142:145], v[200:203], v[90:93]
	v_mfma_f32_16x16x32_bf16 v[82:85], v[134:137], v[222:225], v[82:85]
	v_mfma_f32_16x16x32_bf16 v[74:77], v[142:145], v[222:225], v[74:77]
	s_setprio 0
	s_setprio 1
	v_mfma_f32_16x16x32_bf16 v[118:121], v[146:149], v[172:175], v[118:121]
	v_mfma_f32_16x16x32_bf16 v[114:117], v[154:157], v[172:175], v[114:117]
	v_mfma_f32_16x16x32_bf16 v[102:105], v[146:149], v[188:191], v[102:105]
	v_mfma_f32_16x16x32_bf16 v[94:97], v[154:157], v[188:191], v[94:97]
	v_mfma_f32_16x16x32_bf16 v[86:89], v[146:149], v[196:199], v[86:89]
	v_mfma_f32_16x16x32_bf16 v[78:81], v[154:157], v[196:199], v[78:81]
	v_mfma_f32_16x16x32_bf16 v[70:73], v[146:149], v[204:207], v[70:73]
	v_mfma_f32_16x16x32_bf16 v[66:69], v[154:157], v[204:207], v[66:69]
	v_mfma_f32_16x16x32_bf16 v[118:121], v[150:153], v[176:179], v[118:121]
	v_mfma_f32_16x16x32_bf16 v[114:117], v[168:171], v[176:179], v[114:117]
	v_mfma_f32_16x16x32_bf16 v[102:105], v[150:153], v[192:195], v[102:105]
	v_mfma_f32_16x16x32_bf16 v[94:97], v[168:171], v[192:195], v[94:97]
	s_barrier
	v_mfma_f32_16x16x32_bf16 v[86:89], v[150:153], v[200:203], v[86:89]
	v_mfma_f32_16x16x32_bf16 v[78:81], v[168:171], v[200:203], v[78:81]
	v_mfma_f32_16x16x32_bf16 v[70:73], v[150:153], v[222:225], v[70:73]
	v_mfma_f32_16x16x32_bf16 v[66:69], v[168:171], v[222:225], v[66:69]
	s_setprio 0
	s_add_i32 s6, s6, s37
	v_lshl_add_u64 v[180:181], s[4:5], 0, v[0:1]
	s_mov_b32 m0, s6
	ds_read_b128 v[172:175], v187 offset:16384
	ds_read_b128 v[176:179], v187 offset:17408
	ds_read_b128 v[188:191], v187 offset:18432
	ds_read_b128 v[192:195], v187 offset:19456
	ds_read_b128 v[196:199], v187 offset:20480
	ds_read_b128 v[200:203], v187 offset:21504
	ds_read_b128 v[204:207], v187 offset:22528
	ds_read_b128 v[222:225], v187 offset:23552
	global_load_lds_dwordx4 v[180:181], off
	s_add_i32 m0, s6, 0x2000
	v_lshl_add_u64 v[208:209], s[4:5], 0, v[160:161]
	s_add_u32 s4, s4, s84
	s_addc_u32 s5, s5, 0
	s_add_i32 s6, s7, s37
	global_load_lds_dwordx4 v[208:209], off
	v_lshl_add_u64 v[226:227], s[4:5], 0, v[0:1]
	s_mov_b32 m0, s6
	v_lshl_add_u64 v[228:229], s[4:5], 0, v[160:161]
	global_load_lds_dwordx4 v[226:227], off
	s_add_i32 m0, s6, 0x2000
	v_lshl_add_u64 v[230:231], s[34:35], 0, v[162:163]
	global_load_lds_dwordx4 v[228:229], off
	s_mov_b32 m0, s38
	v_lshl_add_u64 v[232:233], s[34:35], 0, v[158:159]
	global_load_lds_dwordx4 v[230:231], off
	s_mov_b32 m0, s39
	s_nop 0
	global_load_lds_dwordx4 v[232:233], off
	s_waitcnt vmcnt(8)
	s_waitcnt lgkmcnt(0)
	s_barrier
	s_setprio 1
	s_waitcnt lgkmcnt(0)
	v_mfma_f32_16x16x32_bf16 v[62:65], v[130:133], v[172:175], v[62:65]
	v_mfma_f32_16x16x32_bf16 v[58:61], v[138:141], v[172:175], v[58:61]
	v_mfma_f32_16x16x32_bf16 v[46:49], v[130:133], v[188:191], v[46:49]
	v_mfma_f32_16x16x32_bf16 v[42:45], v[138:141], v[188:191], v[42:45]
	v_mfma_f32_16x16x32_bf16 v[34:37], v[130:133], v[196:199], v[34:37]
	v_mfma_f32_16x16x32_bf16 v[26:29], v[138:141], v[196:199], v[26:29]
	v_mfma_f32_16x16x32_bf16 v[18:21], v[130:133], v[204:207], v[18:21]
	v_mfma_f32_16x16x32_bf16 v[10:13], v[138:141], v[204:207], v[10:13]
	v_mfma_f32_16x16x32_bf16 v[62:65], v[134:137], v[176:179], v[62:65]
	v_mfma_f32_16x16x32_bf16 v[58:61], v[142:145], v[176:179], v[58:61]
	v_mfma_f32_16x16x32_bf16 v[46:49], v[134:137], v[192:195], v[46:49]
	v_mfma_f32_16x16x32_bf16 v[42:45], v[142:145], v[192:195], v[42:45]
	v_mfma_f32_16x16x32_bf16 v[34:37], v[134:137], v[200:203], v[34:37]
	v_mfma_f32_16x16x32_bf16 v[26:29], v[142:145], v[200:203], v[26:29]
	v_mfma_f32_16x16x32_bf16 v[18:21], v[134:137], v[222:225], v[18:21]
	v_mfma_f32_16x16x32_bf16 v[10:13], v[142:145], v[222:225], v[10:13]
	s_setprio 0
	s_setprio 1
	v_mfma_f32_16x16x32_bf16 v[54:57], v[146:149], v[172:175], v[54:57]
	v_mfma_f32_16x16x32_bf16 v[50:53], v[154:157], v[172:175], v[50:53]
	v_mfma_f32_16x16x32_bf16 v[38:41], v[146:149], v[188:191], v[38:41]
	v_mfma_f32_16x16x32_bf16 v[30:33], v[154:157], v[188:191], v[30:33]
	v_mfma_f32_16x16x32_bf16 v[22:25], v[146:149], v[196:199], v[22:25]
	v_mfma_f32_16x16x32_bf16 v[14:17], v[154:157], v[196:199], v[14:17]
	v_mfma_f32_16x16x32_bf16 v[6:9], v[146:149], v[204:207], v[6:9]
	v_mfma_f32_16x16x32_bf16 v[2:5], v[154:157], v[204:207], v[2:5]
	v_mfma_f32_16x16x32_bf16 v[54:57], v[150:153], v[176:179], v[54:57]
	v_mfma_f32_16x16x32_bf16 v[50:53], v[168:171], v[176:179], v[50:53]
	v_mfma_f32_16x16x32_bf16 v[38:41], v[150:153], v[192:195], v[38:41]
	v_mfma_f32_16x16x32_bf16 v[30:33], v[168:171], v[192:195], v[30:33]
	s_barrier
	v_mfma_f32_16x16x32_bf16 v[22:25], v[150:153], v[200:203], v[22:25]
	v_mfma_f32_16x16x32_bf16 v[14:17], v[168:171], v[200:203], v[14:17]
	v_mfma_f32_16x16x32_bf16 v[6:9], v[150:153], v[222:225], v[6:9]
	v_mfma_f32_16x16x32_bf16 v[2:5], v[168:171], v[222:225], v[2:5]
	s_setprio 0
	s_add_i32 s6, 0, 0x18000
	s_add_i32 s7, 0, 0x1c000
	v_add_u32_e32 v142, s6, v184
	v_add_u32_e32 v168, s7, v184
	ds_read_b128 v[130:133], v142
	ds_read_b128 v[134:137], v142 offset:1024
	ds_read_b128 v[138:141], v142 offset:2048
	ds_read_b128 v[142:145], v142 offset:3072
	ds_read_b128 v[146:149], v168
	ds_read_b128 v[150:153], v168 offset:1024
	ds_read_b128 v[154:157], v168 offset:2048
	ds_read_b128 v[168:171], v168 offset:3072
	s_add_u32 s4, s34, s84
	s_addc_u32 s5, s35, 0
	s_mov_b32 m0, s45
	v_lshl_add_u64 v[234:235], s[4:5], 0, v[162:163]
	ds_read_b128 v[172:175], v187 offset:32768
	ds_read_b128 v[176:179], v187 offset:33792
	ds_read_b128 v[188:191], v187 offset:34816
	ds_read_b128 v[192:195], v187 offset:35840
	ds_read_b128 v[196:199], v187 offset:36864
	ds_read_b128 v[200:203], v187 offset:37888
	ds_read_b128 v[204:207], v187 offset:38912
	ds_read_b128 v[222:225], v187 offset:39936
	global_load_lds_dwordx4 v[234:235], off
	v_lshl_add_u64 v[234:235], s[4:5], 0, v[158:159]
	s_mov_b32 m0, s46
	s_nop 0
	global_load_lds_dwordx4 v[234:235], off
	s_waitcnt vmcnt(8)
	s_waitcnt lgkmcnt(0)
	s_barrier
	s_setprio 1
	s_waitcnt lgkmcnt(0)
	v_mfma_f32_16x16x32_bf16 v[126:129], v[130:133], v[172:175], v[126:129]
	v_mfma_f32_16x16x32_bf16 v[122:125], v[138:141], v[172:175], v[122:125]
	v_mfma_f32_16x16x32_bf16 v[110:113], v[130:133], v[188:191], v[110:113]
	v_mfma_f32_16x16x32_bf16 v[106:109], v[138:141], v[188:191], v[106:109]
	v_mfma_f32_16x16x32_bf16 v[98:101], v[130:133], v[196:199], v[98:101]
	v_mfma_f32_16x16x32_bf16 v[90:93], v[138:141], v[196:199], v[90:93]
	v_mfma_f32_16x16x32_bf16 v[82:85], v[130:133], v[204:207], v[82:85]
	v_mfma_f32_16x16x32_bf16 v[74:77], v[138:141], v[204:207], v[74:77]
	v_mfma_f32_16x16x32_bf16 v[126:129], v[134:137], v[176:179], v[126:129]
	v_mfma_f32_16x16x32_bf16 v[122:125], v[142:145], v[176:179], v[122:125]
	v_mfma_f32_16x16x32_bf16 v[110:113], v[134:137], v[192:195], v[110:113]
	v_mfma_f32_16x16x32_bf16 v[106:109], v[142:145], v[192:195], v[106:109]
	v_mfma_f32_16x16x32_bf16 v[98:101], v[134:137], v[200:203], v[98:101]
	v_mfma_f32_16x16x32_bf16 v[90:93], v[142:145], v[200:203], v[90:93]
	v_mfma_f32_16x16x32_bf16 v[82:85], v[134:137], v[222:225], v[82:85]
	v_mfma_f32_16x16x32_bf16 v[74:77], v[142:145], v[222:225], v[74:77]
	s_setprio 0
	s_setprio 1
	v_mfma_f32_16x16x32_bf16 v[118:121], v[146:149], v[172:175], v[118:121]
	v_mfma_f32_16x16x32_bf16 v[114:117], v[154:157], v[172:175], v[114:117]
	v_mfma_f32_16x16x32_bf16 v[102:105], v[146:149], v[188:191], v[102:105]
	v_mfma_f32_16x16x32_bf16 v[94:97], v[154:157], v[188:191], v[94:97]
	v_mfma_f32_16x16x32_bf16 v[86:89], v[146:149], v[196:199], v[86:89]
	v_mfma_f32_16x16x32_bf16 v[78:81], v[154:157], v[196:199], v[78:81]
	v_mfma_f32_16x16x32_bf16 v[70:73], v[146:149], v[204:207], v[70:73]
	v_mfma_f32_16x16x32_bf16 v[66:69], v[154:157], v[204:207], v[66:69]
	v_mfma_f32_16x16x32_bf16 v[118:121], v[150:153], v[176:179], v[118:121]
	v_mfma_f32_16x16x32_bf16 v[114:117], v[168:171], v[176:179], v[114:117]
	v_mfma_f32_16x16x32_bf16 v[102:105], v[150:153], v[192:195], v[102:105]
	v_mfma_f32_16x16x32_bf16 v[94:97], v[168:171], v[192:195], v[94:97]
	s_barrier
	v_mfma_f32_16x16x32_bf16 v[86:89], v[150:153], v[200:203], v[86:89]
	v_mfma_f32_16x16x32_bf16 v[78:81], v[168:171], v[200:203], v[78:81]
	v_mfma_f32_16x16x32_bf16 v[70:73], v[150:153], v[222:225], v[70:73]
	v_mfma_f32_16x16x32_bf16 v[66:69], v[168:171], v[222:225], v[66:69]
	s_setprio 0
	s_add_i32 s4, s6, s37
	v_lshl_add_u64 v[180:181], v[180:181], 0, s[82:83]
	s_mov_b32 m0, s4
	ds_read_b128 v[172:175], v187 offset:49152
	ds_read_b128 v[176:179], v187 offset:50176
	ds_read_b128 v[188:191], v187 offset:51200
	ds_read_b128 v[192:195], v187 offset:52224
	ds_read_b128 v[196:199], v187 offset:53248
	ds_read_b128 v[200:203], v187 offset:54272
	ds_read_b128 v[204:207], v187 offset:55296
	ds_read_b128 v[222:225], v187 offset:56320
	global_load_lds_dwordx4 v[180:181], off
	v_lshl_add_u64 v[180:181], v[208:209], 0, s[82:83]
	s_add_i32 m0, s4, 0x2000
	s_add_i32 s4, s7, s37
	global_load_lds_dwordx4 v[180:181], off
	v_lshl_add_u64 v[180:181], v[226:227], 0, s[82:83]
	s_mov_b32 m0, s4
	s_nop 0
	global_load_lds_dwordx4 v[180:181], off
	v_lshl_add_u64 v[180:181], v[228:229], 0, s[82:83]
	s_add_i32 m0, s4, 0x2000
	s_nop 0
	global_load_lds_dwordx4 v[180:181], off
	v_lshl_add_u64 v[180:181], v[230:231], 0, s[82:83]
	s_mov_b32 m0, s51
	s_nop 0
	global_load_lds_dwordx4 v[180:181], off
	v_lshl_add_u64 v[180:181], v[232:233], 0, s[82:83]
	s_mov_b32 m0, s52
	s_nop 0
	global_load_lds_dwordx4 v[180:181], off
	s_waitcnt vmcnt(8)
	s_waitcnt lgkmcnt(0)
	s_barrier
	s_setprio 1
	s_waitcnt lgkmcnt(0)
	v_mfma_f32_16x16x32_bf16 v[62:65], v[130:133], v[172:175], v[62:65]
	v_mfma_f32_16x16x32_bf16 v[58:61], v[138:141], v[172:175], v[58:61]
	v_mfma_f32_16x16x32_bf16 v[46:49], v[130:133], v[188:191], v[46:49]
	v_mfma_f32_16x16x32_bf16 v[42:45], v[138:141], v[188:191], v[42:45]
	v_mfma_f32_16x16x32_bf16 v[34:37], v[130:133], v[196:199], v[34:37]
	v_mfma_f32_16x16x32_bf16 v[26:29], v[138:141], v[196:199], v[26:29]
	v_mfma_f32_16x16x32_bf16 v[18:21], v[130:133], v[204:207], v[18:21]
	v_mfma_f32_16x16x32_bf16 v[10:13], v[138:141], v[204:207], v[10:13]
	v_mfma_f32_16x16x32_bf16 v[62:65], v[134:137], v[176:179], v[62:65]
	v_mfma_f32_16x16x32_bf16 v[58:61], v[142:145], v[176:179], v[58:61]
	v_mfma_f32_16x16x32_bf16 v[46:49], v[134:137], v[192:195], v[46:49]
	v_mfma_f32_16x16x32_bf16 v[42:45], v[142:145], v[192:195], v[42:45]
	v_mfma_f32_16x16x32_bf16 v[34:37], v[134:137], v[200:203], v[34:37]
	v_mfma_f32_16x16x32_bf16 v[26:29], v[142:145], v[200:203], v[26:29]
	v_mfma_f32_16x16x32_bf16 v[18:21], v[134:137], v[222:225], v[18:21]
	v_mfma_f32_16x16x32_bf16 v[10:13], v[142:145], v[222:225], v[10:13]
	s_setprio 0
	s_setprio 1
	v_mfma_f32_16x16x32_bf16 v[54:57], v[146:149], v[172:175], v[54:57]
	v_mfma_f32_16x16x32_bf16 v[50:53], v[154:157], v[172:175], v[50:53]
	v_mfma_f32_16x16x32_bf16 v[38:41], v[146:149], v[188:191], v[38:41]
	v_mfma_f32_16x16x32_bf16 v[30:33], v[154:157], v[188:191], v[30:33]
	v_mfma_f32_16x16x32_bf16 v[22:25], v[146:149], v[196:199], v[22:25]
	v_mfma_f32_16x16x32_bf16 v[14:17], v[154:157], v[196:199], v[14:17]
	v_mfma_f32_16x16x32_bf16 v[6:9], v[146:149], v[204:207], v[6:9]
	v_mfma_f32_16x16x32_bf16 v[2:5], v[154:157], v[204:207], v[2:5]
	v_mfma_f32_16x16x32_bf16 v[54:57], v[150:153], v[176:179], v[54:57]
	v_mfma_f32_16x16x32_bf16 v[50:53], v[168:171], v[176:179], v[50:53]
	v_mfma_f32_16x16x32_bf16 v[38:41], v[150:153], v[192:195], v[38:41]
	v_mfma_f32_16x16x32_bf16 v[30:33], v[168:171], v[192:195], v[30:33]
	s_barrier
	v_mfma_f32_16x16x32_bf16 v[22:25], v[150:153], v[200:203], v[22:25]
	v_mfma_f32_16x16x32_bf16 v[14:17], v[168:171], v[200:203], v[14:17]
	v_mfma_f32_16x16x32_bf16 v[6:9], v[150:153], v[222:225], v[6:9]
	v_mfma_f32_16x16x32_bf16 v[2:5], v[168:171], v[222:225], v[2:5]
	s_setprio 0
	s_add_u32 s30, s30, 0x100
	s_addc_u32 s31, s31, 0
	s_add_u32 s42, s42, 0x100
	s_addc_u32 s43, s43, 0
	s_cmp_ge_u32 s59, s48
	s_mov_b32 s34, s59
	s_cbranch_scc0 .LBB0_452
	s_and_b64 vcc, exec, s[24:25]
	s_cbranch_vccz .LBB0_455
	s_barrier

.LBB0_489:
	s_add_u32 s4, s30, 0xfffc0080
	s_addc_u32 s5, s31, -1
	s_add_i32 s6, 0, 0x10000
	s_cmp_eq_u32 s59, 12
	s_cselect_b32 s37, s25, s5
	s_cselect_b32 s36, s66, s4
	s_cselect_b32 s35, s23, s69
	s_cselect_b32 s34, s67, s68
	s_add_i32 s7, 0, 0x14000
	v_add_u32_e32 v156, s6, v146
	v_add_u32_e32 v172, s7, v146
	ds_read_b128 v[140:143], v156
	ds_read_b128 v[148:151], v156 offset:1024
	ds_read_b128 v[152:155], v156 offset:2048
	ds_read_b128 v[156:159], v156 offset:3072
	ds_read_b128 v[160:163], v172
	ds_read_b128 v[164:167], v172 offset:1024
	ds_read_b128 v[168:171], v172 offset:2048
	ds_read_b128 v[172:175], v172 offset:3072
	v_lshl_add_u64 v[208:209], s[30:31], 0, v[136:137]
	s_add_i32 m0, s43, 0xc000
	ds_read_b128 v[176:179], v147
	ds_read_b128 v[180:183], v147 offset:1024
	ds_read_b128 v[184:187], v147 offset:2048
	ds_read_b128 v[188:191], v147 offset:3072
	ds_read_b128 v[192:195], v147 offset:4096
	ds_read_b128 v[196:199], v147 offset:5120
	ds_read_b128 v[200:203], v147 offset:6144
	ds_read_b128 v[204:207], v147 offset:7168
	global_load_lds_dwordx4 v[208:209], off
	v_lshl_add_u64 v[208:209], s[30:31], 0, v[138:139]
	s_add_i32 m0, s43, 0xe000
	s_nop 0
	global_load_lds_dwordx4 v[208:209], off
	s_waitcnt vmcnt(8)
	s_waitcnt lgkmcnt(0)
	s_barrier
	s_setprio 1
	s_waitcnt lgkmcnt(0)
	v_mfma_f32_16x16x32_bf16 v[126:129], v[140:143], v[176:179], v[126:129]
	v_mfma_f32_16x16x32_bf16 v[122:125], v[152:155], v[176:179], v[122:125]
	v_mfma_f32_16x16x32_bf16 v[118:121], v[140:143], v[184:187], v[118:121]
	v_mfma_f32_16x16x32_bf16 v[110:113], v[152:155], v[184:187], v[110:113]
	v_mfma_f32_16x16x32_bf16 v[102:105], v[140:143], v[192:195], v[102:105]
	v_mfma_f32_16x16x32_bf16 v[94:97], v[152:155], v[192:195], v[94:97]
	v_mfma_f32_16x16x32_bf16 v[86:89], v[140:143], v[200:203], v[86:89]
	v_mfma_f32_16x16x32_bf16 v[78:81], v[152:155], v[200:203], v[78:81]
	v_mfma_f32_16x16x32_bf16 v[126:129], v[148:151], v[180:183], v[126:129]
	v_mfma_f32_16x16x32_bf16 v[122:125], v[156:159], v[180:183], v[122:125]
	v_mfma_f32_16x16x32_bf16 v[118:121], v[148:151], v[188:191], v[118:121]
	v_mfma_f32_16x16x32_bf16 v[110:113], v[156:159], v[188:191], v[110:113]
	v_mfma_f32_16x16x32_bf16 v[102:105], v[148:151], v[196:199], v[102:105]
	v_mfma_f32_16x16x32_bf16 v[94:97], v[156:159], v[196:199], v[94:97]
	v_mfma_f32_16x16x32_bf16 v[86:89], v[148:151], v[204:207], v[86:89]
	v_mfma_f32_16x16x32_bf16 v[78:81], v[156:159], v[204:207], v[78:81]
	s_setprio 0
	s_setprio 1
	v_mfma_f32_16x16x32_bf16 v[114:117], v[160:163], v[176:179], v[114:117]
	v_mfma_f32_16x16x32_bf16 v[106:109], v[168:171], v[176:179], v[106:109]
	v_mfma_f32_16x16x32_bf16 v[98:101], v[160:163], v[184:187], v[98:101]
	v_mfma_f32_16x16x32_bf16 v[90:93], v[168:171], v[184:187], v[90:93]
	v_mfma_f32_16x16x32_bf16 v[82:85], v[160:163], v[192:195], v[82:85]
	v_mfma_f32_16x16x32_bf16 v[74:77], v[168:171], v[192:195], v[74:77]
	v_mfma_f32_16x16x32_bf16 v[70:73], v[160:163], v[200:203], v[70:73]
	v_mfma_f32_16x16x32_bf16 v[66:69], v[168:171], v[200:203], v[66:69]
	v_mfma_f32_16x16x32_bf16 v[114:117], v[164:167], v[180:183], v[114:117]
	v_mfma_f32_16x16x32_bf16 v[106:109], v[172:175], v[180:183], v[106:109]
	v_mfma_f32_16x16x32_bf16 v[98:101], v[164:167], v[188:191], v[98:101]
	v_mfma_f32_16x16x32_bf16 v[90:93], v[172:175], v[188:191], v[90:93]
	s_barrier
	v_mfma_f32_16x16x32_bf16 v[82:85], v[164:167], v[196:199], v[82:85]
	v_mfma_f32_16x16x32_bf16 v[74:77], v[172:175], v[196:199], v[74:77]
	v_mfma_f32_16x16x32_bf16 v[70:73], v[164:167], v[204:207], v[70:73]
	v_mfma_f32_16x16x32_bf16 v[66:69], v[172:175], v[204:207], v[66:69]
	s_setprio 0
	s_add_i32 s4, s6, s38
	v_lshl_add_u64 v[208:209], s[34:35], 0, v[0:1]
	s_mov_b32 m0, s4
	ds_read_b128 v[176:179], v147 offset:16384
	ds_read_b128 v[180:183], v147 offset:17408
	ds_read_b128 v[184:187], v147 offset:18432
	ds_read_b128 v[188:191], v147 offset:19456
	ds_read_b128 v[192:195], v147 offset:20480
	ds_read_b128 v[196:199], v147 offset:21504
	ds_read_b128 v[200:203], v147 offset:22528
	ds_read_b128 v[204:207], v147 offset:23552
	global_load_lds_dwordx4 v[208:209], off
	s_add_i32 m0, s4, 0x2000
	s_add_u32 s4, s34, 0x40000
	v_lshl_add_u64 v[222:223], s[34:35], 0, v[132:133]
	s_addc_u32 s5, s35, 0
	s_add_i32 s6, s7, s38
	global_load_lds_dwordx4 v[222:223], off
	v_lshl_add_u64 v[224:225], s[4:5], 0, v[0:1]
	s_mov_b32 m0, s6
	v_lshl_add_u64 v[226:227], s[36:37], 0, v[130:131]
	global_load_lds_dwordx4 v[224:225], off
	v_lshl_add_u64 v[224:225], s[4:5], 0, v[132:133]
	s_add_i32 m0, s6, 0x2000
	s_nop 0
	global_load_lds_dwordx4 v[224:225], off
	v_lshl_add_u64 v[224:225], s[36:37], 0, v[134:135]
	s_mov_b32 m0, s43
	s_nop 0
	global_load_lds_dwordx4 v[224:225], off
	s_mov_b32 m0, s44
	s_nop 0
	global_load_lds_dwordx4 v[226:227], off
	s_waitcnt vmcnt(8)
	s_waitcnt lgkmcnt(0)
	s_barrier
	s_setprio 1
	s_waitcnt lgkmcnt(0)
	v_mfma_f32_16x16x32_bf16 v[62:65], v[140:143], v[176:179], v[62:65]
	v_mfma_f32_16x16x32_bf16 v[58:61], v[152:155], v[176:179], v[58:61]
	v_mfma_f32_16x16x32_bf16 v[54:57], v[140:143], v[184:187], v[54:57]
	v_mfma_f32_16x16x32_bf16 v[46:49], v[152:155], v[184:187], v[46:49]
	v_mfma_f32_16x16x32_bf16 v[38:41], v[140:143], v[192:195], v[38:41]
	v_mfma_f32_16x16x32_bf16 v[30:33], v[152:155], v[192:195], v[30:33]
	v_mfma_f32_16x16x32_bf16 v[22:25], v[140:143], v[200:203], v[22:25]
	v_mfma_f32_16x16x32_bf16 v[14:17], v[152:155], v[200:203], v[14:17]
	v_mfma_f32_16x16x32_bf16 v[62:65], v[148:151], v[180:183], v[62:65]
	v_mfma_f32_16x16x32_bf16 v[58:61], v[156:159], v[180:183], v[58:61]
	v_mfma_f32_16x16x32_bf16 v[54:57], v[148:151], v[188:191], v[54:57]
	v_mfma_f32_16x16x32_bf16 v[46:49], v[156:159], v[188:191], v[46:49]
	v_mfma_f32_16x16x32_bf16 v[38:41], v[148:151], v[196:199], v[38:41]
	v_mfma_f32_16x16x32_bf16 v[30:33], v[156:159], v[196:199], v[30:33]
	v_mfma_f32_16x16x32_bf16 v[22:25], v[148:151], v[204:207], v[22:25]
	v_mfma_f32_16x16x32_bf16 v[14:17], v[156:159], v[204:207], v[14:17]
	s_setprio 0
	s_setprio 1
	v_mfma_f32_16x16x32_bf16 v[50:53], v[160:163], v[176:179], v[50:53]
	v_mfma_f32_16x16x32_bf16 v[42:45], v[168:171], v[176:179], v[42:45]
	v_mfma_f32_16x16x32_bf16 v[34:37], v[160:163], v[184:187], v[34:37]
	v_mfma_f32_16x16x32_bf16 v[26:29], v[168:171], v[184:187], v[26:29]
	v_mfma_f32_16x16x32_bf16 v[18:21], v[160:163], v[192:195], v[18:21]
	v_mfma_f32_16x16x32_bf16 v[10:13], v[168:171], v[192:195], v[10:13]
	v_mfma_f32_16x16x32_bf16 v[6:9], v[160:163], v[200:203], v[6:9]
	v_mfma_f32_16x16x32_bf16 v[2:5], v[168:171], v[200:203], v[2:5]
	v_mfma_f32_16x16x32_bf16 v[50:53], v[164:167], v[180:183], v[50:53]
	v_mfma_f32_16x16x32_bf16 v[42:45], v[172:175], v[180:183], v[42:45]
	v_mfma_f32_16x16x32_bf16 v[34:37], v[164:167], v[188:191], v[34:37]
	v_mfma_f32_16x16x32_bf16 v[26:29], v[172:175], v[188:191], v[26:29]
	s_barrier
	v_mfma_f32_16x16x32_bf16 v[18:21], v[164:167], v[196:199], v[18:21]
	v_mfma_f32_16x16x32_bf16 v[10:13], v[172:175], v[196:199], v[10:13]
	v_mfma_f32_16x16x32_bf16 v[6:9], v[164:167], v[204:207], v[6:9]
	v_mfma_f32_16x16x32_bf16 v[2:5], v[172:175], v[204:207], v[2:5]
	s_setprio 0
	s_add_i32 s6, 0, 0x18000
	s_add_i32 s7, 0, 0x1c000
	v_add_u32_e32 v156, s6, v146
	v_add_u32_e32 v172, s7, v146
	ds_read_b128 v[140:143], v156
	ds_read_b128 v[148:151], v156 offset:1024
	ds_read_b128 v[152:155], v156 offset:2048
	ds_read_b128 v[156:159], v156 offset:3072
	ds_read_b128 v[160:163], v172
	ds_read_b128 v[164:167], v172 offset:1024
	ds_read_b128 v[168:171], v172 offset:2048
	ds_read_b128 v[172:175], v172 offset:3072
	s_add_u32 s4, s36, 0x40000
	s_addc_u32 s5, s37, 0
	s_mov_b32 m0, s45
	v_lshl_add_u64 v[228:229], s[4:5], 0, v[134:135]
	ds_read_b128 v[176:179], v147 offset:32768
	ds_read_b128 v[180:183], v147 offset:33792
	ds_read_b128 v[184:187], v147 offset:34816
	ds_read_b128 v[188:191], v147 offset:35840
	ds_read_b128 v[192:195], v147 offset:36864
	ds_read_b128 v[196:199], v147 offset:37888
	ds_read_b128 v[200:203], v147 offset:38912
	ds_read_b128 v[204:207], v147 offset:39936
	global_load_lds_dwordx4 v[228:229], off
	v_lshl_add_u64 v[228:229], s[4:5], 0, v[130:131]
	s_mov_b32 m0, s46
	s_nop 0
	global_load_lds_dwordx4 v[228:229], off
	s_waitcnt vmcnt(8)
	s_waitcnt lgkmcnt(0)
	s_barrier
	s_setprio 1
	s_waitcnt lgkmcnt(0)
	v_mfma_f32_16x16x32_bf16 v[126:129], v[140:143], v[176:179], v[126:129]
	v_mfma_f32_16x16x32_bf16 v[122:125], v[152:155], v[176:179], v[122:125]
	v_mfma_f32_16x16x32_bf16 v[118:121], v[140:143], v[184:187], v[118:121]
	v_mfma_f32_16x16x32_bf16 v[110:113], v[152:155], v[184:187], v[110:113]
	v_mfma_f32_16x16x32_bf16 v[102:105], v[140:143], v[192:195], v[102:105]
	v_mfma_f32_16x16x32_bf16 v[94:97], v[152:155], v[192:195], v[94:97]
	v_mfma_f32_16x16x32_bf16 v[86:89], v[140:143], v[200:203], v[86:89]
	v_mfma_f32_16x16x32_bf16 v[78:81], v[152:155], v[200:203], v[78:81]
	v_mfma_f32_16x16x32_bf16 v[126:129], v[148:151], v[180:183], v[126:129]
	v_mfma_f32_16x16x32_bf16 v[122:125], v[156:159], v[180:183], v[122:125]
	v_mfma_f32_16x16x32_bf16 v[118:121], v[148:151], v[188:191], v[118:121]
	v_mfma_f32_16x16x32_bf16 v[110:113], v[156:159], v[188:191], v[110:113]
	v_mfma_f32_16x16x32_bf16 v[102:105], v[148:151], v[196:199], v[102:105]
	v_mfma_f32_16x16x32_bf16 v[94:97], v[156:159], v[196:199], v[94:97]
	v_mfma_f32_16x16x32_bf16 v[86:89], v[148:151], v[204:207], v[86:89]
	v_mfma_f32_16x16x32_bf16 v[78:81], v[156:159], v[204:207], v[78:81]
	s_setprio 0
	s_setprio 1
	v_mfma_f32_16x16x32_bf16 v[114:117], v[160:163], v[176:179], v[114:117]
	v_mfma_f32_16x16x32_bf16 v[106:109], v[168:171], v[176:179], v[106:109]
	v_mfma_f32_16x16x32_bf16 v[98:101], v[160:163], v[184:187], v[98:101]
	v_mfma_f32_16x16x32_bf16 v[90:93], v[168:171], v[184:187], v[90:93]
	v_mfma_f32_16x16x32_bf16 v[82:85], v[160:163], v[192:195], v[82:85]
	v_mfma_f32_16x16x32_bf16 v[74:77], v[168:171], v[192:195], v[74:77]
	v_mfma_f32_16x16x32_bf16 v[70:73], v[160:163], v[200:203], v[70:73]
	v_mfma_f32_16x16x32_bf16 v[66:69], v[168:171], v[200:203], v[66:69]
	v_mfma_f32_16x16x32_bf16 v[114:117], v[164:167], v[180:183], v[114:117]
	v_mfma_f32_16x16x32_bf16 v[106:109], v[172:175], v[180:183], v[106:109]
	v_mfma_f32_16x16x32_bf16 v[98:101], v[164:167], v[188:191], v[98:101]
	v_mfma_f32_16x16x32_bf16 v[90:93], v[172:175], v[188:191], v[90:93]
	s_barrier
	v_mfma_f32_16x16x32_bf16 v[82:85], v[164:167], v[196:199], v[82:85]
	v_mfma_f32_16x16x32_bf16 v[74:77], v[172:175], v[196:199], v[74:77]
	v_mfma_f32_16x16x32_bf16 v[70:73], v[164:167], v[204:207], v[70:73]
	v_mfma_f32_16x16x32_bf16 v[66:69], v[172:175], v[204:207], v[66:69]
	s_setprio 0
	s_add_i32 s4, s6, s38
	v_lshl_add_u64 v[208:209], v[208:209], 0, s[82:83]
	s_mov_b32 m0, s4
	ds_read_b128 v[176:179], v147 offset:49152
	ds_read_b128 v[180:183], v147 offset:50176
	ds_read_b128 v[184:187], v147 offset:51200
	ds_read_b128 v[188:191], v147 offset:52224
	ds_read_b128 v[192:195], v147 offset:53248
	ds_read_b128 v[196:199], v147 offset:54272
	ds_read_b128 v[200:203], v147 offset:55296
	ds_read_b128 v[204:207], v147 offset:56320
	global_load_lds_dwordx4 v[208:209], off
	s_add_i32 m0, s4, 0x2000
	s_add_u32 s4, s34, 0x40080
	v_lshl_add_u64 v[208:209], v[222:223], 0, s[82:83]
	s_addc_u32 s5, s35, 0
	s_add_i32 s6, s7, s38
	global_load_lds_dwordx4 v[208:209], off
	v_lshl_add_u64 v[208:209], s[4:5], 0, v[0:1]
	s_mov_b32 m0, s6
	s_nop 0
	global_load_lds_dwordx4 v[208:209], off
	v_lshl_add_u64 v[208:209], s[4:5], 0, v[132:133]
	s_add_i32 m0, s6, 0x2000
	s_nop 0
	global_load_lds_dwordx4 v[208:209], off
	v_lshl_add_u64 v[208:209], v[224:225], 0, s[82:83]
	s_mov_b32 m0, s49
	s_nop 0
	global_load_lds_dwordx4 v[208:209], off
	v_lshl_add_u64 v[208:209], v[226:227], 0, s[82:83]
	s_mov_b32 m0, s50
	s_nop 0
	global_load_lds_dwordx4 v[208:209], off
	s_waitcnt vmcnt(8)
	s_waitcnt lgkmcnt(0)
	s_barrier
	s_setprio 1
	s_waitcnt lgkmcnt(0)
	v_mfma_f32_16x16x32_bf16 v[62:65], v[140:143], v[176:179], v[62:65]
	v_mfma_f32_16x16x32_bf16 v[58:61], v[152:155], v[176:179], v[58:61]
	v_mfma_f32_16x16x32_bf16 v[54:57], v[140:143], v[184:187], v[54:57]
	v_mfma_f32_16x16x32_bf16 v[46:49], v[152:155], v[184:187], v[46:49]
	v_mfma_f32_16x16x32_bf16 v[38:41], v[140:143], v[192:195], v[38:41]
	v_mfma_f32_16x16x32_bf16 v[30:33], v[152:155], v[192:195], v[30:33]
	v_mfma_f32_16x16x32_bf16 v[22:25], v[140:143], v[200:203], v[22:25]
	v_mfma_f32_16x16x32_bf16 v[14:17], v[152:155], v[200:203], v[14:17]
	v_mfma_f32_16x16x32_bf16 v[62:65], v[148:151], v[180:183], v[62:65]
	v_mfma_f32_16x16x32_bf16 v[58:61], v[156:159], v[180:183], v[58:61]
	v_mfma_f32_16x16x32_bf16 v[54:57], v[148:151], v[188:191], v[54:57]
	v_mfma_f32_16x16x32_bf16 v[46:49], v[156:159], v[188:191], v[46:49]
	v_mfma_f32_16x16x32_bf16 v[38:41], v[148:151], v[196:199], v[38:41]
	v_mfma_f32_16x16x32_bf16 v[30:33], v[156:159], v[196:199], v[30:33]
	v_mfma_f32_16x16x32_bf16 v[22:25], v[148:151], v[204:207], v[22:25]
	v_mfma_f32_16x16x32_bf16 v[14:17], v[156:159], v[204:207], v[14:17]
	s_setprio 0
	s_setprio 1
	v_mfma_f32_16x16x32_bf16 v[50:53], v[160:163], v[176:179], v[50:53]
	v_mfma_f32_16x16x32_bf16 v[42:45], v[168:171], v[176:179], v[42:45]
	v_mfma_f32_16x16x32_bf16 v[34:37], v[160:163], v[184:187], v[34:37]
	v_mfma_f32_16x16x32_bf16 v[26:29], v[168:171], v[184:187], v[26:29]
	v_mfma_f32_16x16x32_bf16 v[18:21], v[160:163], v[192:195], v[18:21]
	v_mfma_f32_16x16x32_bf16 v[10:13], v[168:171], v[192:195], v[10:13]
	v_mfma_f32_16x16x32_bf16 v[6:9], v[160:163], v[200:203], v[6:9]
	v_mfma_f32_16x16x32_bf16 v[2:5], v[168:171], v[200:203], v[2:5]
	v_mfma_f32_16x16x32_bf16 v[50:53], v[164:167], v[180:183], v[50:53]
	v_mfma_f32_16x16x32_bf16 v[42:45], v[172:175], v[180:183], v[42:45]
	v_mfma_f32_16x16x32_bf16 v[34:37], v[164:167], v[188:191], v[34:37]
	v_mfma_f32_16x16x32_bf16 v[26:29], v[172:175], v[188:191], v[26:29]
	s_barrier
	v_mfma_f32_16x16x32_bf16 v[18:21], v[164:167], v[196:199], v[18:21]
	v_mfma_f32_16x16x32_bf16 v[10:13], v[172:175], v[196:199], v[10:13]
	v_mfma_f32_16x16x32_bf16 v[6:9], v[164:167], v[204:207], v[6:9]
	v_mfma_f32_16x16x32_bf16 v[2:5], v[172:175], v[204:207], v[2:5]
	s_setprio 0
	s_add_i32 s59, s59, 2
	s_add_u32 s30, s30, 0x100
	s_addc_u32 s31, s31, 0
	s_add_u32 s68, s68, 0x100
	s_addc_u32 s69, s69, 0
	s_cmp_gt_u32 s59, 13
	s_cbranch_scc0 .LBB0_489
	s_and_b64 vcc, exec, s[20:21]
	s_cbranch_vccz .LBB0_492
	s_barrier
